# U reduction: diagonal sum by quad DPP adds instead of cndmask extraction + 2 transposing stages
# speedup vs baseline: 1.0015x; 1.0015x over previous
; #define PG_ISSUE(BUF, TAB, e0_) do { const int isrc_ = ((e0_) < 64) ? myi0 : myi1; \
;       _Pragma("unroll") for (int e = 0; e < 8; ++e) { const int idx_ = __builtin_amdgcn_readlane(isrc_, ((e0_) + e) & 63); \
;         BUF[e] = *(const u32x4*)((TAB) + (size_t)idx_ * 1024 + lane * 16); } } while (0)
; DEV void peer_gather(const Params& P, int l, int m0, const int* idxs, const float* gs) {
;     ...
;     PG_ISSUE(b0, U, 0);
; #pragma nounroll
;     for (int e0 = 0; e0 < 128; e0 += 16) {
;       PG_ISSUE(b1, U, e0 + 8);
;       PG_U8(b0, 0, e0);
;       if (e0 + 16 < 128) PG_ISSUE(b0, U, e0 + 16); else PG_ISSUE(b0, V, 0);
;       PG_U8(b1, 0, e0 + 8);
;     }
.Lpg0_uloop:
	s_and_b32 s98, s100, 15
	s_add_u32 s92, s100, 1
	s_min_u32 s92, s92, 127
	s_lshr_b32 s93, s92, 4
	s_and_b32 s92, s92, 15
	s_waitcnt lgkmcnt(0)
	ds_bpermute_b32 v142, v249, v134
	ds_bpermute_b32 v143, v250, v134
	s_waitcnt vmcnt(16)
	v_mov_b32_e32 v64, v80
	v_mov_b32_e32 v65, v81
	v_mov_b32_e32 v66, v82
	v_mov_b32_e32 v67, v83
	v_mov_b32_e32 v68, v84
	v_mov_b32_e32 v69, v85
	v_mov_b32_e32 v70, v86
	v_mov_b32_e32 v71, v87
	s_lshl3_add_u32 vcc_lo, s92, s93
	v_lshl_add_u32 v119, vcc_lo, 8, v236
	global_load_dwordx4 v[80:83], v119, s[82:83]
	global_load_dwordx4 v[84:87], v119, s[82:83] offset:16
	v_lshl_or_b32 v240, s93, 21, v235
	s_waitcnt vmcnt(16) lgkmcnt(0)
	ds_bpermute_b32 v244, v251, v134
	ds_bpermute_b32 v245, v252, v134
	v_cvt_scalef32_pk_bf16_fp8 v104, v0, 1.0
	v_cvt_scalef32_pk_bf16_fp8 v106, v4, 1.0
	v_cvt_scalef32_pk_bf16_fp8 v105, v0, 1.0 op_sel:[1,0,0]
	v_cvt_scalef32_pk_bf16_fp8 v107, v4, 1.0 op_sel:[1,0,0]
	v_cvt_scalef32_pk_bf16_fp8 v108, v1, 1.0
	v_cvt_scalef32_pk_bf16_fp8 v109, v1, 1.0 op_sel:[1,0,0]
	v_mfma_f32_4x4x4_16b_bf16 v[72:75], v[104:105], v[64:65], 0
	v_cvt_scalef32_pk_bf16_fp8 v110, v5, 1.0
	v_cvt_scalef32_pk_bf16_fp8 v111, v5, 1.0 op_sel:[1,0,0]
	v_mfma_f32_4x4x4_16b_bf16 v[76:79], v[106:107], v[64:65], 0
	v_cvt_scalef32_pk_bf16_fp8 v104, v2, 1.0
	v_cvt_scalef32_pk_bf16_fp8 v105, v2, 1.0 op_sel:[1,0,0]
	v_mfma_f32_4x4x4_16b_bf16 v[72:75], v[108:109], v[66:67], v[72:75]
	v_cvt_scalef32_pk_bf16_fp8 v106, v6, 1.0
	v_cvt_scalef32_pk_bf16_fp8 v107, v6, 1.0 op_sel:[1,0,0]
	v_mfma_f32_4x4x4_16b_bf16 v[76:79], v[110:111], v[66:67], v[76:79]
	v_cvt_scalef32_pk_bf16_fp8 v108, v3, 1.0
	v_cvt_scalef32_pk_bf16_fp8 v109, v3, 1.0 op_sel:[1,0,0]
	v_mfma_f32_4x4x4_16b_bf16 v[72:75], v[104:105], v[68:69], v[72:75]
	v_cvt_scalef32_pk_bf16_fp8 v110, v7, 1.0
	v_cvt_scalef32_pk_bf16_fp8 v111, v7, 1.0 op_sel:[1,0,0]
	v_mfma_f32_4x4x4_16b_bf16 v[76:79], v[106:107], v[68:69], v[76:79]
	v_and_or_b32 v142, v142, s2, v240
	v_and_or_b32 v143, v143, s2, v240
	global_load_dwordx4 v[0:3], v142, s[80:81]
	global_load_dwordx4 v[4:7], v143, s[80:81]
	s_waitcnt vmcnt(16) lgkmcnt(0)
	ds_bpermute_b32 v142, v253, v134
	ds_bpermute_b32 v143, v254, v134
	v_cvt_scalef32_pk_bf16_fp8 v104, v8, 1.0
	v_cvt_scalef32_pk_bf16_fp8 v105, v8, 1.0 op_sel:[1,0,0]
	v_mfma_f32_4x4x4_16b_bf16 v[72:75], v[108:109], v[70:71], v[72:75]
	v_cvt_scalef32_pk_bf16_fp8 v106, v12, 1.0
	v_cvt_scalef32_pk_bf16_fp8 v107, v12, 1.0 op_sel:[1,0,0]
	v_mfma_f32_4x4x4_16b_bf16 v[76:79], v[110:111], v[70:71], v[76:79]
	v_cvt_scalef32_pk_bf16_fp8 v108, v9, 1.0
	v_cvt_scalef32_pk_bf16_fp8 v110, v13, 1.0
	v_cvt_scalef32_pk_bf16_fp8 v109, v9, 1.0 op_sel:[1,0,0]
	v_cvt_scalef32_pk_bf16_fp8 v111, v13, 1.0 op_sel:[1,0,0]
	v_add_f32_dpp v148, v73, v72 quad_perm:[1,0,3,2] row_mask:0xf bank_mask:0xf
	v_add_f32_dpp v149, v75, v74 quad_perm:[1,0,3,2] row_mask:0xf bank_mask:0xf
	v_add_f32_dpp v150, v76, v77 quad_perm:[1,0,3,2] row_mask:0xf bank_mask:0xf
	v_add_f32_dpp v151, v78, v79 quad_perm:[1,0,3,2] row_mask:0xf bank_mask:0xf
	v_mfma_f32_4x4x4_16b_bf16 v[72:75], v[104:105], v[64:65], 0
	v_add_f32_dpp v88, v149, v148 quad_perm:[2,3,0,1] row_mask:0xf bank_mask:0xf
	v_mfma_f32_4x4x4_16b_bf16 v[76:79], v[106:107], v[64:65], 0
	v_add_f32_dpp v89, v151, v150 quad_perm:[2,3,0,1] row_mask:0xf bank_mask:0xf
	v_cvt_scalef32_pk_bf16_fp8 v104, v10, 1.0
	v_cvt_scalef32_pk_bf16_fp8 v105, v10, 1.0 op_sel:[1,0,0]
	v_mfma_f32_4x4x4_16b_bf16 v[72:75], v[108:109], v[66:67], v[72:75]
	v_cvt_scalef32_pk_bf16_fp8 v106, v14, 1.0
	v_cvt_scalef32_pk_bf16_fp8 v107, v14, 1.0 op_sel:[1,0,0]
	v_mfma_f32_4x4x4_16b_bf16 v[76:79], v[110:111], v[66:67], v[76:79]
	v_cvt_scalef32_pk_bf16_fp8 v108, v11, 1.0
	v_cvt_scalef32_pk_bf16_fp8 v109, v11, 1.0 op_sel:[1,0,0]
	v_mfma_f32_4x4x4_16b_bf16 v[72:75], v[104:105], v[68:69], v[72:75]
	v_cvt_scalef32_pk_bf16_fp8 v110, v15, 1.0
	v_cvt_scalef32_pk_bf16_fp8 v111, v15, 1.0 op_sel:[1,0,0]
	v_mfma_f32_4x4x4_16b_bf16 v[76:79], v[106:107], v[68:69], v[76:79]
	v_and_or_b32 v244, v244, s2, v240
	v_and_or_b32 v245, v245, s2, v240
	global_load_dwordx4 v[8:11], v244, s[80:81]
	global_load_dwordx4 v[12:15], v245, s[80:81]
	s_waitcnt vmcnt(16) lgkmcnt(0)
	ds_bpermute_b32 v244, v255, v134
	ds_bpermute_b32 v245, v153, v134
	v_cvt_scalef32_pk_bf16_fp8 v104, v16, 1.0
	v_cvt_scalef32_pk_bf16_fp8 v105, v16, 1.0 op_sel:[1,0,0]
	v_mfma_f32_4x4x4_16b_bf16 v[72:75], v[108:109], v[70:71], v[72:75]
	v_cvt_scalef32_pk_bf16_fp8 v106, v20, 1.0
	v_cvt_scalef32_pk_bf16_fp8 v107, v20, 1.0 op_sel:[1,0,0]
	v_mfma_f32_4x4x4_16b_bf16 v[76:79], v[110:111], v[70:71], v[76:79]
	v_cvt_scalef32_pk_bf16_fp8 v108, v17, 1.0
	v_cvt_scalef32_pk_bf16_fp8 v110, v21, 1.0
	v_cvt_scalef32_pk_bf16_fp8 v109, v17, 1.0 op_sel:[1,0,0]
	v_cvt_scalef32_pk_bf16_fp8 v111, v21, 1.0 op_sel:[1,0,0]
	v_add_f32_dpp v148, v75, v74 quad_perm:[1,0,3,2] row_mask:0xf bank_mask:0xf
	v_add_f32_dpp v149, v73, v72 quad_perm:[1,0,3,2] row_mask:0xf bank_mask:0xf
	v_add_f32_dpp v150, v78, v79 quad_perm:[1,0,3,2] row_mask:0xf bank_mask:0xf
	v_add_f32_dpp v151, v76, v77 quad_perm:[1,0,3,2] row_mask:0xf bank_mask:0xf
	v_mfma_f32_4x4x4_16b_bf16 v[72:75], v[104:105], v[64:65], 0
	v_add_f32_dpp v90, v149, v148 quad_perm:[2,3,0,1] row_mask:0xf bank_mask:0xf
	v_mfma_f32_4x4x4_16b_bf16 v[76:79], v[106:107], v[64:65], 0
	v_add_f32_dpp v91, v151, v150 quad_perm:[2,3,0,1] row_mask:0xf bank_mask:0xf
	v_cvt_scalef32_pk_bf16_fp8 v104, v18, 1.0
	v_cvt_scalef32_pk_bf16_fp8 v105, v18, 1.0 op_sel:[1,0,0]
	v_mfma_f32_4x4x4_16b_bf16 v[72:75], v[108:109], v[66:67], v[72:75]
	v_cvt_scalef32_pk_bf16_fp8 v106, v22, 1.0
	v_cvt_scalef32_pk_bf16_fp8 v107, v22, 1.0 op_sel:[1,0,0]
	v_mfma_f32_4x4x4_16b_bf16 v[76:79], v[110:111], v[66:67], v[76:79]
	v_cvt_scalef32_pk_bf16_fp8 v108, v19, 1.0
	v_cvt_scalef32_pk_bf16_fp8 v109, v19, 1.0 op_sel:[1,0,0]
	v_mfma_f32_4x4x4_16b_bf16 v[72:75], v[104:105], v[68:69], v[72:75]
	v_cvt_scalef32_pk_bf16_fp8 v110, v23, 1.0
	v_cvt_scalef32_pk_bf16_fp8 v111, v23, 1.0 op_sel:[1,0,0]
	v_mfma_f32_4x4x4_16b_bf16 v[76:79], v[106:107], v[68:69], v[76:79]
	v_and_or_b32 v142, v142, s2, v240
	v_and_or_b32 v143, v143, s2, v240
	global_load_dwordx4 v[16:19], v142, s[80:81]
	global_load_dwordx4 v[20:23], v143, s[80:81]
	s_waitcnt vmcnt(16) lgkmcnt(0)
; #define PG_ISSUE(BUF, TAB, e0_) do { const int isrc_ = ((e0_) < 64) ? myi0 : myi1; \
;       _Pragma("unroll") for (int e = 0; e < 8; ++e) { const int idx_ = __builtin_amdgcn_readlane(isrc_, ((e0_) + e) & 63); \
;         BUF[e] = *(const u32x4*)((TAB) + (size_t)idx_ * 1024 + lane * 16); } } while (0)
; DEV void peer_gather(const Params& P, int l, int m0, const int* idxs, const float* gs) {
;     ...
;     PG_ISSUE(b0, U, 0);
; #pragma nounroll
;     for (int e0 = 0; e0 < 128; e0 += 16) {
;       PG_ISSUE(b1, U, e0 + 8);
;       PG_U8(b0, 0, e0);
;       if (e0 + 16 < 128) PG_ISSUE(b0, U, e0 + 16); else PG_ISSUE(b0, V, 0);
;       PG_U8(b1, 0, e0 + 8);
;     }
	ds_bpermute_b32 v142, v249, v135
	ds_bpermute_b32 v143, v250, v135
	v_cvt_scalef32_pk_bf16_fp8 v104, v24, 1.0
	v_cvt_scalef32_pk_bf16_fp8 v105, v24, 1.0 op_sel:[1,0,0]
	v_mfma_f32_4x4x4_16b_bf16 v[72:75], v[108:109], v[70:71], v[72:75]
	v_cvt_scalef32_pk_bf16_fp8 v106, v28, 1.0
	v_cvt_scalef32_pk_bf16_fp8 v107, v28, 1.0 op_sel:[1,0,0]
	v_mfma_f32_4x4x4_16b_bf16 v[76:79], v[110:111], v[70:71], v[76:79]
	v_cvt_scalef32_pk_bf16_fp8 v108, v25, 1.0
	v_cvt_scalef32_pk_bf16_fp8 v110, v29, 1.0
	v_cvt_scalef32_pk_bf16_fp8 v109, v25, 1.0 op_sel:[1,0,0]
	v_cvt_scalef32_pk_bf16_fp8 v111, v29, 1.0 op_sel:[1,0,0]
	v_add_f32_dpp v148, v73, v72 quad_perm:[1,0,3,2] row_mask:0xf bank_mask:0xf
	v_add_f32_dpp v149, v75, v74 quad_perm:[1,0,3,2] row_mask:0xf bank_mask:0xf
	v_add_f32_dpp v150, v76, v77 quad_perm:[1,0,3,2] row_mask:0xf bank_mask:0xf
	v_add_f32_dpp v151, v78, v79 quad_perm:[1,0,3,2] row_mask:0xf bank_mask:0xf
	v_mfma_f32_4x4x4_16b_bf16 v[72:75], v[104:105], v[64:65], 0
	v_add_f32_dpp v92, v149, v148 quad_perm:[2,3,0,1] row_mask:0xf bank_mask:0xf
	v_mfma_f32_4x4x4_16b_bf16 v[76:79], v[106:107], v[64:65], 0
	v_add_f32_dpp v93, v151, v150 quad_perm:[2,3,0,1] row_mask:0xf bank_mask:0xf
	v_cvt_scalef32_pk_bf16_fp8 v104, v26, 1.0
	v_cvt_scalef32_pk_bf16_fp8 v105, v26, 1.0 op_sel:[1,0,0]
	v_mfma_f32_4x4x4_16b_bf16 v[72:75], v[108:109], v[66:67], v[72:75]
	v_cvt_scalef32_pk_bf16_fp8 v106, v30, 1.0
	v_cvt_scalef32_pk_bf16_fp8 v107, v30, 1.0 op_sel:[1,0,0]
	v_mfma_f32_4x4x4_16b_bf16 v[76:79], v[110:111], v[66:67], v[76:79]
	v_cvt_scalef32_pk_bf16_fp8 v108, v27, 1.0
	v_cvt_scalef32_pk_bf16_fp8 v109, v27, 1.0 op_sel:[1,0,0]
	v_mfma_f32_4x4x4_16b_bf16 v[72:75], v[104:105], v[68:69], v[72:75]
	v_cvt_scalef32_pk_bf16_fp8 v110, v31, 1.0
	v_cvt_scalef32_pk_bf16_fp8 v111, v31, 1.0 op_sel:[1,0,0]
	v_mfma_f32_4x4x4_16b_bf16 v[76:79], v[106:107], v[68:69], v[76:79]
	v_and_or_b32 v244, v244, s2, v240
	v_and_or_b32 v245, v245, s2, v240
	global_load_dwordx4 v[24:27], v244, s[80:81]
	global_load_dwordx4 v[28:31], v245, s[80:81]
	s_waitcnt vmcnt(16) lgkmcnt(0)
	ds_bpermute_b32 v244, v251, v135
	ds_bpermute_b32 v245, v252, v135
	v_cvt_scalef32_pk_bf16_fp8 v104, v32, 1.0
	v_cvt_scalef32_pk_bf16_fp8 v105, v32, 1.0 op_sel:[1,0,0]
	v_mfma_f32_4x4x4_16b_bf16 v[72:75], v[108:109], v[70:71], v[72:75]
	v_cvt_scalef32_pk_bf16_fp8 v106, v36, 1.0
	v_cvt_scalef32_pk_bf16_fp8 v107, v36, 1.0 op_sel:[1,0,0]
	v_mfma_f32_4x4x4_16b_bf16 v[76:79], v[110:111], v[70:71], v[76:79]
	v_cvt_scalef32_pk_bf16_fp8 v108, v33, 1.0
	v_cvt_scalef32_pk_bf16_fp8 v110, v37, 1.0
	v_cvt_scalef32_pk_bf16_fp8 v109, v33, 1.0 op_sel:[1,0,0]
	v_cvt_scalef32_pk_bf16_fp8 v111, v37, 1.0 op_sel:[1,0,0]
	v_add_f32_dpp v148, v75, v74 quad_perm:[1,0,3,2] row_mask:0xf bank_mask:0xf
	v_add_f32_dpp v149, v73, v72 quad_perm:[1,0,3,2] row_mask:0xf bank_mask:0xf
	v_add_f32_dpp v150, v78, v79 quad_perm:[1,0,3,2] row_mask:0xf bank_mask:0xf
	v_add_f32_dpp v151, v76, v77 quad_perm:[1,0,3,2] row_mask:0xf bank_mask:0xf
	v_mfma_f32_4x4x4_16b_bf16 v[72:75], v[104:105], v[64:65], 0
	v_add_f32_dpp v94, v149, v148 quad_perm:[2,3,0,1] row_mask:0xf bank_mask:0xf
	v_mfma_f32_4x4x4_16b_bf16 v[76:79], v[106:107], v[64:65], 0
	v_add_f32_dpp v95, v151, v150 quad_perm:[2,3,0,1] row_mask:0xf bank_mask:0xf
	v_cvt_scalef32_pk_bf16_fp8 v104, v34, 1.0
	v_cvt_scalef32_pk_bf16_fp8 v105, v34, 1.0 op_sel:[1,0,0]
	v_mfma_f32_4x4x4_16b_bf16 v[72:75], v[108:109], v[66:67], v[72:75]
	v_cvt_scalef32_pk_bf16_fp8 v106, v38, 1.0
	v_cvt_scalef32_pk_bf16_fp8 v107, v38, 1.0 op_sel:[1,0,0]
	v_mfma_f32_4x4x4_16b_bf16 v[76:79], v[110:111], v[66:67], v[76:79]
	v_cvt_scalef32_pk_bf16_fp8 v108, v35, 1.0
	v_cvt_scalef32_pk_bf16_fp8 v109, v35, 1.0 op_sel:[1,0,0]
	v_mfma_f32_4x4x4_16b_bf16 v[72:75], v[104:105], v[68:69], v[72:75]
	v_cvt_scalef32_pk_bf16_fp8 v110, v39, 1.0
	v_cvt_scalef32_pk_bf16_fp8 v111, v39, 1.0 op_sel:[1,0,0]
	v_mfma_f32_4x4x4_16b_bf16 v[76:79], v[106:107], v[68:69], v[76:79]
	v_and_or_b32 v142, v142, s2, v240
	v_and_or_b32 v143, v143, s2, v240
	global_load_dwordx4 v[32:35], v142, s[80:81]
	global_load_dwordx4 v[36:39], v143, s[80:81]
	s_waitcnt vmcnt(16) lgkmcnt(0)
	ds_bpermute_b32 v142, v253, v135
	ds_bpermute_b32 v143, v254, v135
	v_cvt_scalef32_pk_bf16_fp8 v104, v40, 1.0
	v_cvt_scalef32_pk_bf16_fp8 v105, v40, 1.0 op_sel:[1,0,0]
	v_mfma_f32_4x4x4_16b_bf16 v[72:75], v[108:109], v[70:71], v[72:75]
	v_cvt_scalef32_pk_bf16_fp8 v106, v44, 1.0
	v_cvt_scalef32_pk_bf16_fp8 v107, v44, 1.0 op_sel:[1,0,0]
	v_mfma_f32_4x4x4_16b_bf16 v[76:79], v[110:111], v[70:71], v[76:79]
	v_cvt_scalef32_pk_bf16_fp8 v108, v41, 1.0
	v_cvt_scalef32_pk_bf16_fp8 v110, v45, 1.0
	v_cvt_scalef32_pk_bf16_fp8 v109, v41, 1.0 op_sel:[1,0,0]
	v_cvt_scalef32_pk_bf16_fp8 v111, v45, 1.0 op_sel:[1,0,0]
	v_add_f32_dpp v148, v73, v72 quad_perm:[1,0,3,2] row_mask:0xf bank_mask:0xf
	v_add_f32_dpp v149, v75, v74 quad_perm:[1,0,3,2] row_mask:0xf bank_mask:0xf
	v_add_f32_dpp v150, v76, v77 quad_perm:[1,0,3,2] row_mask:0xf bank_mask:0xf
	v_add_f32_dpp v151, v78, v79 quad_perm:[1,0,3,2] row_mask:0xf bank_mask:0xf
	v_mfma_f32_4x4x4_16b_bf16 v[72:75], v[104:105], v[64:65], 0
	v_add_f32_dpp v96, v149, v148 quad_perm:[2,3,0,1] row_mask:0xf bank_mask:0xf
	v_mfma_f32_4x4x4_16b_bf16 v[76:79], v[106:107], v[64:65], 0
	v_add_f32_dpp v97, v151, v150 quad_perm:[2,3,0,1] row_mask:0xf bank_mask:0xf
	v_cvt_scalef32_pk_bf16_fp8 v104, v42, 1.0
	v_cvt_scalef32_pk_bf16_fp8 v105, v42, 1.0 op_sel:[1,0,0]
	v_mfma_f32_4x4x4_16b_bf16 v[72:75], v[108:109], v[66:67], v[72:75]
	v_cvt_scalef32_pk_bf16_fp8 v106, v46, 1.0
	v_cvt_scalef32_pk_bf16_fp8 v107, v46, 1.0 op_sel:[1,0,0]
	v_mfma_f32_4x4x4_16b_bf16 v[76:79], v[110:111], v[66:67], v[76:79]
	v_cvt_scalef32_pk_bf16_fp8 v108, v43, 1.0
	v_cvt_scalef32_pk_bf16_fp8 v109, v43, 1.0 op_sel:[1,0,0]
	v_mfma_f32_4x4x4_16b_bf16 v[72:75], v[104:105], v[68:69], v[72:75]
	v_cvt_scalef32_pk_bf16_fp8 v110, v47, 1.0
	v_cvt_scalef32_pk_bf16_fp8 v111, v47, 1.0 op_sel:[1,0,0]
	v_mfma_f32_4x4x4_16b_bf16 v[76:79], v[106:107], v[68:69], v[76:79]
	v_and_or_b32 v244, v244, s2, v240
	v_and_or_b32 v245, v245, s2, v240
	global_load_dwordx4 v[40:43], v244, s[80:81]
	global_load_dwordx4 v[44:47], v245, s[80:81]
	s_waitcnt vmcnt(16) lgkmcnt(0)
; #define PG_ISSUE(BUF, TAB, e0_) do { const int isrc_ = ((e0_) < 64) ? myi0 : myi1; \
;       _Pragma("unroll") for (int e = 0; e < 8; ++e) { const int idx_ = __builtin_amdgcn_readlane(isrc_, ((e0_) + e) & 63); \
;         BUF[e] = *(const u32x4*)((TAB) + (size_t)idx_ * 1024 + lane * 16); } } while (0)
; DEV void peer_gather(const Params& P, int l, int m0, const int* idxs, const float* gs) {
;     ...
;     PG_ISSUE(b0, U, 0);
; #pragma nounroll
;     for (int e0 = 0; e0 < 128; e0 += 16) {
;       PG_ISSUE(b1, U, e0 + 8);
;       PG_U8(b0, 0, e0);
;       if (e0 + 16 < 128) PG_ISSUE(b0, U, e0 + 16); else PG_ISSUE(b0, V, 0);
;       PG_U8(b1, 0, e0 + 8);
;     }
	ds_bpermute_b32 v244, v255, v135
	ds_bpermute_b32 v245, v153, v135
	v_cvt_scalef32_pk_bf16_fp8 v104, v48, 1.0
	v_cvt_scalef32_pk_bf16_fp8 v105, v48, 1.0 op_sel:[1,0,0]
	v_mfma_f32_4x4x4_16b_bf16 v[72:75], v[108:109], v[70:71], v[72:75]
	v_cvt_scalef32_pk_bf16_fp8 v106, v52, 1.0
	v_cvt_scalef32_pk_bf16_fp8 v107, v52, 1.0 op_sel:[1,0,0]
	v_mfma_f32_4x4x4_16b_bf16 v[76:79], v[110:111], v[70:71], v[76:79]
	v_cvt_scalef32_pk_bf16_fp8 v108, v49, 1.0
	v_cvt_scalef32_pk_bf16_fp8 v110, v53, 1.0
	v_cvt_scalef32_pk_bf16_fp8 v109, v49, 1.0 op_sel:[1,0,0]
	v_cvt_scalef32_pk_bf16_fp8 v111, v53, 1.0 op_sel:[1,0,0]
	v_add_f32_dpp v148, v75, v74 quad_perm:[1,0,3,2] row_mask:0xf bank_mask:0xf
	v_add_f32_dpp v149, v73, v72 quad_perm:[1,0,3,2] row_mask:0xf bank_mask:0xf
	v_add_f32_dpp v150, v78, v79 quad_perm:[1,0,3,2] row_mask:0xf bank_mask:0xf
	v_add_f32_dpp v151, v76, v77 quad_perm:[1,0,3,2] row_mask:0xf bank_mask:0xf
	v_mfma_f32_4x4x4_16b_bf16 v[72:75], v[104:105], v[64:65], 0
	v_add_f32_dpp v98, v149, v148 quad_perm:[2,3,0,1] row_mask:0xf bank_mask:0xf
	v_mfma_f32_4x4x4_16b_bf16 v[76:79], v[106:107], v[64:65], 0
	v_add_f32_dpp v99, v151, v150 quad_perm:[2,3,0,1] row_mask:0xf bank_mask:0xf
	v_cvt_scalef32_pk_bf16_fp8 v104, v50, 1.0
	v_cvt_scalef32_pk_bf16_fp8 v105, v50, 1.0 op_sel:[1,0,0]
	v_mfma_f32_4x4x4_16b_bf16 v[72:75], v[108:109], v[66:67], v[72:75]
	v_cvt_scalef32_pk_bf16_fp8 v106, v54, 1.0
	v_cvt_scalef32_pk_bf16_fp8 v107, v54, 1.0 op_sel:[1,0,0]
	v_mfma_f32_4x4x4_16b_bf16 v[76:79], v[110:111], v[66:67], v[76:79]
	v_cvt_scalef32_pk_bf16_fp8 v108, v51, 1.0
	v_cvt_scalef32_pk_bf16_fp8 v109, v51, 1.0 op_sel:[1,0,0]
	v_mfma_f32_4x4x4_16b_bf16 v[72:75], v[104:105], v[68:69], v[72:75]
	v_cvt_scalef32_pk_bf16_fp8 v110, v55, 1.0
	v_cvt_scalef32_pk_bf16_fp8 v111, v55, 1.0 op_sel:[1,0,0]
	v_mfma_f32_4x4x4_16b_bf16 v[76:79], v[106:107], v[68:69], v[76:79]
	v_and_or_b32 v142, v142, s2, v240
	v_and_or_b32 v143, v143, s2, v240
	global_load_dwordx4 v[48:51], v142, s[80:81]
	global_load_dwordx4 v[52:55], v143, s[80:81]
	s_waitcnt vmcnt(16) lgkmcnt(0)
	v_cvt_scalef32_pk_bf16_fp8 v104, v56, 1.0
	v_cvt_scalef32_pk_bf16_fp8 v105, v56, 1.0 op_sel:[1,0,0]
	v_mfma_f32_4x4x4_16b_bf16 v[72:75], v[108:109], v[70:71], v[72:75]
	v_cvt_scalef32_pk_bf16_fp8 v106, v60, 1.0
	v_cvt_scalef32_pk_bf16_fp8 v107, v60, 1.0 op_sel:[1,0,0]
	v_mfma_f32_4x4x4_16b_bf16 v[76:79], v[110:111], v[70:71], v[76:79]
	v_cvt_scalef32_pk_bf16_fp8 v108, v57, 1.0
	v_cvt_scalef32_pk_bf16_fp8 v110, v61, 1.0
	v_cvt_scalef32_pk_bf16_fp8 v109, v57, 1.0 op_sel:[1,0,0]
	v_cvt_scalef32_pk_bf16_fp8 v111, v61, 1.0 op_sel:[1,0,0]
	v_add_f32_dpp v148, v73, v72 quad_perm:[1,0,3,2] row_mask:0xf bank_mask:0xf
	v_add_f32_dpp v149, v75, v74 quad_perm:[1,0,3,2] row_mask:0xf bank_mask:0xf
	v_add_f32_dpp v150, v76, v77 quad_perm:[1,0,3,2] row_mask:0xf bank_mask:0xf
	v_add_f32_dpp v151, v78, v79 quad_perm:[1,0,3,2] row_mask:0xf bank_mask:0xf
	v_mfma_f32_4x4x4_16b_bf16 v[72:75], v[104:105], v[64:65], 0
	v_add_f32_dpp v100, v149, v148 quad_perm:[2,3,0,1] row_mask:0xf bank_mask:0xf
	v_mfma_f32_4x4x4_16b_bf16 v[76:79], v[106:107], v[64:65], 0
	v_add_f32_dpp v101, v151, v150 quad_perm:[2,3,0,1] row_mask:0xf bank_mask:0xf
	v_cvt_scalef32_pk_bf16_fp8 v104, v58, 1.0
	v_cvt_scalef32_pk_bf16_fp8 v105, v58, 1.0 op_sel:[1,0,0]
	v_mfma_f32_4x4x4_16b_bf16 v[72:75], v[108:109], v[66:67], v[72:75]
	v_cvt_scalef32_pk_bf16_fp8 v106, v62, 1.0
	v_cvt_scalef32_pk_bf16_fp8 v107, v62, 1.0 op_sel:[1,0,0]
	v_mfma_f32_4x4x4_16b_bf16 v[76:79], v[110:111], v[66:67], v[76:79]
	v_cvt_scalef32_pk_bf16_fp8 v108, v59, 1.0
	v_cvt_scalef32_pk_bf16_fp8 v109, v59, 1.0 op_sel:[1,0,0]
	v_mfma_f32_4x4x4_16b_bf16 v[72:75], v[104:105], v[68:69], v[72:75]
	v_cvt_scalef32_pk_bf16_fp8 v110, v63, 1.0
	v_cvt_scalef32_pk_bf16_fp8 v111, v63, 1.0 op_sel:[1,0,0]
	v_mfma_f32_4x4x4_16b_bf16 v[76:79], v[106:107], v[68:69], v[76:79]
	v_and_or_b32 v244, v244, s2, v240
	v_and_or_b32 v245, v245, s2, v240
	global_load_dwordx4 v[56:59], v244, s[80:81]
	global_load_dwordx4 v[60:63], v245, s[80:81]
	v_mfma_f32_4x4x4_16b_bf16 v[72:75], v[108:109], v[70:71], v[72:75]
	v_mfma_f32_4x4x4_16b_bf16 v[76:79], v[110:111], v[70:71], v[76:79]
	s_add_u32 s92, s100, 2
	s_and_b32 s92, s92, 15
	v_lshl_add_u32 v116, s92, 9, v246
	ds_read_b32 v134, v116
	ds_read_b32 v135, v116 offset:256
	v_lshl_add_u32 v117, s98, 9, v247
	ds_read_b32 v136, v117
	ds_read_b32 v137, v117 offset:256
	v_add_f32_dpp v148, v75, v74 quad_perm:[1,0,3,2] row_mask:0xf bank_mask:0xf
	v_add_f32_dpp v149, v73, v72 quad_perm:[1,0,3,2] row_mask:0xf bank_mask:0xf
	v_add_f32_dpp v150, v78, v79 quad_perm:[1,0,3,2] row_mask:0xf bank_mask:0xf
	v_add_f32_dpp v151, v76, v77 quad_perm:[1,0,3,2] row_mask:0xf bank_mask:0xf
	v_add_f32_dpp v102, v149, v148 quad_perm:[2,3,0,1] row_mask:0xf bank_mask:0xf
	s_nop 0
	v_add_f32_dpp v103, v151, v150 quad_perm:[2,3,0,1] row_mask:0xf bank_mask:0xf
	v_cndmask_b32_e64 v144, v88, v89, s[88:89]
	v_cndmask_b32_e64 v145, v90, v91, s[88:89]
	v_cndmask_b32_e64 v88, v144, v145, s[86:87]
	v_cndmask_b32_e64 v144, v92, v93, s[88:89]
	v_cndmask_b32_e64 v145, v94, v95, s[88:89]
	v_cndmask_b32_e64 v92, v144, v145, s[86:87]
	v_cndmask_b32_e64 v144, v96, v97, s[88:89]
	v_cndmask_b32_e64 v145, v98, v99, s[88:89]
	v_cndmask_b32_e64 v96, v144, v145, s[86:87]
	v_cndmask_b32_e64 v144, v100, v101, s[88:89]
	v_cndmask_b32_e64 v145, v102, v103, s[88:89]
	v_cndmask_b32_e64 v100, v144, v145, s[86:87]
	v_cndmask_b32_e64 v144, v88, v92, s[90:91]
	v_cndmask_b32_e64 v145, v92, v88, s[90:91]
	v_cndmask_b32_e64 v146, v96, v100, s[90:91]
	v_cndmask_b32_e64 v147, v100, v96, s[90:91]
	s_nop 1
	v_add_f32_dpp v88, v145, v144 row_shl:4 row_mask:0xf bank_mask:0x5
	v_add_f32_dpp v88, v145, v144 row_shr:4 row_mask:0xf bank_mask:0xa
	v_add_f32_dpp v96, v147, v146 row_shl:4 row_mask:0xf bank_mask:0x5
	v_add_f32_dpp v96, v147, v146 row_shr:4 row_mask:0xf bank_mask:0xa
	s_nop 0
	ds_bpermute_b32 v144, v239, v88
	ds_bpermute_b32 v145, v239, v96
	s_waitcnt lgkmcnt(0)
	v_add_f32_e32 v136, v136, v144
	v_add_f32_e32 v137, v137, v145
	ds_write_b32 v117, v136
	ds_write_b32 v117, v137 offset:256
	s_add_u32 s100, s100, 1
	s_cmp_lt_u32 s100, 128
	s_cbranch_scc1 .Lpg0_uloop
	s_waitcnt vmcnt(0) lgkmcnt(0)
	s_mov_b32 s2, 0
